# barriers b1..b5: acquire invalidate issued right behind the arrive atomic (overlaps its round trip), on stack18
# baseline (speedup 1.0000x reference)
; __device__ __forceinline__ unsigned xb_ld(unsigned* p)              { return __hip_atomic_load(p, __ATOMIC_RELAXED, __HIP_MEMORY_SCOPE_AGENT); }
; __device__ __forceinline__ unsigned xb_add(unsigned* p, unsigned v) { return __hip_atomic_fetch_add(p, v, __ATOMIC_RELAXED, __HIP_MEMORY_SCOPE_AGENT); }
; #define XB_SPIN(cond, bar) do { unsigned _sp = 0; while (cond) { __builtin_amdgcn_s_sleep(1); \
;     if ((++_sp & 255u) == 0u) { if (xb_ld(&(bar)[XB_TMO])) break; if (_sp > XB_SPIN_CAP) { atomicAdd(&(bar)[XB_TMO], 1u); break; } } } } while (0)
; __device__ __forceinline__ void xcd_barrier(const XcdBarrier& b) {
;     ...
;         unsigned nloc = b.st[0], nx = b.st[1];
;         if (nloc == 0u) { xcd_barrier_complete(bar, b.x, nloc, nx); b.st[0] = nloc; b.st[1] = nx; }
;         const unsigned old = xb_add(&bar[XB_XSUB(b.x)], 1u);
;         const unsigned gen = old / nloc;
;         if (old + 1u == (gen + 1u) * nloc) {
;             __builtin_amdgcn_fence(__ATOMIC_RELEASE, "agent");
;             asm volatile("s_waitcnt vmcnt(0)" ::: "memory");
;             const unsigned og = xb_add(&bar[XB_TOP], 1u);
;             const unsigned tg = og / nx;
;             if (og + 1u == (tg + 1u) * nx) xb_add(&bar[XB_TOPGEN], 1u);
;             else XB_SPIN(xb_ld(&bar[XB_TOPGEN]) == tg, bar);
;             __builtin_amdgcn_fence(__ATOMIC_ACQUIRE, "agent");
;             asm volatile("s_waitcnt vmcnt(0)" ::: "memory");
;         } else {
;             XB_SPIN(xb_ld(&bar[XB_TOPGEN]) == gen, bar);
;             __builtin_amdgcn_fence(__ATOMIC_ACQUIRE, "agent");
;             asm volatile("s_waitcnt vmcnt(0)" ::: "memory");
;         }
.LBB0_333:
	v_readlane_b32 s4, v253, 35
	v_readlane_b32 s5, v253, 36
	v_cvt_f32_u32_e32 v1, v2
	v_sub_u32_e32 v4, 0, v2
	v_rcp_iflag_f32_e32 v1, v1
	s_nop 1
	global_atomic_add v3, v177, v238, s[4:5] sc0
	buffer_inv sc1
	v_mul_f32_e32 v1, 0x4f7ffffe, v1
	v_cvt_u32_f32_e32 v1, v1
	v_mul_lo_u32 v4, v4, v1
	v_mul_hi_u32 v4, v1, v4
	v_add_u32_e32 v1, v1, v4
	s_waitcnt vmcnt(0)
	v_mul_hi_u32 v1, v3, v1
	v_mul_lo_u32 v4, v1, v2
	v_sub_u32_e32 v4, v3, v4
	v_add_u32_e32 v5, 1, v1
	v_cmp_ge_u32_e32 vcc, v4, v2
	v_add_u32_e32 v3, 1, v3
	s_nop 0
	v_cndmask_b32_e32 v1, v1, v5, vcc
	v_sub_u32_e32 v5, v4, v2
	v_cndmask_b32_e32 v4, v4, v5, vcc
	v_add_u32_e32 v5, 1, v1
	v_cmp_ge_u32_e32 vcc, v4, v2
	s_nop 1
	v_cndmask_b32_e32 v1, v1, v5, vcc
	v_mul_lo_u32 v4, v2, v1
	v_add_u32_e32 v2, v4, v2
	v_cmp_ne_u32_e32 vcc, v3, v2
	s_waitcnt lgkmcnt(0)
	v_add_u32_e32 v4, 1, v1
	v_mul_lo_u32 v4, v4, v0
	v_readlane_b32 s98, v253, 39
	v_readlane_b32 s99, v253, 40
	s_nop 4
	s_cbranch_vccnz .Lxb_b1_nl
	buffer_wbl2 sc1
	s_waitcnt vmcnt(0)
	global_atomic_add v177, v238, s[98:99]
	s_mov_b32 s100, 0

; __device__ __forceinline__ unsigned xb_ld(unsigned* p)              { return __hip_atomic_load(p, __ATOMIC_RELAXED, __HIP_MEMORY_SCOPE_AGENT); }
; #define XB_SPIN(cond, bar) do { unsigned _sp = 0; while (cond) { __builtin_amdgcn_s_sleep(1); \
;     if ((++_sp & 255u) == 0u) { if (xb_ld(&(bar)[XB_TMO])) break; if (_sp > XB_SPIN_CAP) { atomicAdd(&(bar)[XB_TMO], 1u); break; } } } } while (0)
; __device__ __forceinline__ void xcd_barrier(const XcdBarrier& b) {
;     ...
;         } else {
;             XB_SPIN(xb_ld(&bar[XB_TOPGEN]) == gen, bar);
;             __builtin_amdgcn_fence(__ATOMIC_ACQUIRE, "agent");
;             asm volatile("s_waitcnt vmcnt(0)" ::: "memory");
.Lxb_b1_nl:
	v_add_u32_e32 v6, 1, v1
	s_mov_b32 s100, 0

; __device__ __forceinline__ unsigned xb_ld(unsigned* p)              { return __hip_atomic_load(p, __ATOMIC_RELAXED, __HIP_MEMORY_SCOPE_AGENT); }
; __device__ __forceinline__ unsigned xb_add(unsigned* p, unsigned v) { return __hip_atomic_fetch_add(p, v, __ATOMIC_RELAXED, __HIP_MEMORY_SCOPE_AGENT); }
; #define XB_SPIN(cond, bar) do { unsigned _sp = 0; while (cond) { __builtin_amdgcn_s_sleep(1); \
;     if ((++_sp & 255u) == 0u) { if (xb_ld(&(bar)[XB_TMO])) break; if (_sp > XB_SPIN_CAP) { atomicAdd(&(bar)[XB_TMO], 1u); break; } } } } while (0)
; __device__ __forceinline__ void xcd_barrier(const XcdBarrier& b) {
;     ...
;         unsigned nloc = b.st[0], nx = b.st[1];
;         if (nloc == 0u) { xcd_barrier_complete(bar, b.x, nloc, nx); b.st[0] = nloc; b.st[1] = nx; }
;         const unsigned old = xb_add(&bar[XB_XSUB(b.x)], 1u);
;         const unsigned gen = old / nloc;
;         if (old + 1u == (gen + 1u) * nloc) {
;             __builtin_amdgcn_fence(__ATOMIC_RELEASE, "agent");
;             asm volatile("s_waitcnt vmcnt(0)" ::: "memory");
;             const unsigned og = xb_add(&bar[XB_TOP], 1u);
;             const unsigned tg = og / nx;
;             if (og + 1u == (tg + 1u) * nx) xb_add(&bar[XB_TOPGEN], 1u);
;             else XB_SPIN(xb_ld(&bar[XB_TOPGEN]) == tg, bar);
;             __builtin_amdgcn_fence(__ATOMIC_ACQUIRE, "agent");
;             asm volatile("s_waitcnt vmcnt(0)" ::: "memory");
;         } else {
;             XB_SPIN(xb_ld(&bar[XB_TOPGEN]) == gen, bar);
;             __builtin_amdgcn_fence(__ATOMIC_ACQUIRE, "agent");
;             asm volatile("s_waitcnt vmcnt(0)" ::: "memory");
;         }
.LBB0_509:
	v_readlane_b32 s4, v253, 35
	v_readlane_b32 s5, v253, 36
	v_cvt_f32_u32_e32 v1, v2
	v_sub_u32_e32 v4, 0, v2
	v_rcp_iflag_f32_e32 v1, v1
	s_nop 1
	global_atomic_add v3, v177, v238, s[4:5] sc0
	buffer_inv sc1
	v_mul_f32_e32 v1, 0x4f7ffffe, v1
	v_cvt_u32_f32_e32 v1, v1
	v_mul_lo_u32 v4, v4, v1
	v_mul_hi_u32 v4, v1, v4
	v_add_u32_e32 v1, v1, v4
	s_waitcnt vmcnt(0)
	v_mul_hi_u32 v1, v3, v1
	v_mul_lo_u32 v4, v1, v2
	v_sub_u32_e32 v4, v3, v4
	v_add_u32_e32 v5, 1, v1
	v_cmp_ge_u32_e32 vcc, v4, v2
	v_add_u32_e32 v3, 1, v3
	s_nop 0
	v_cndmask_b32_e32 v1, v1, v5, vcc
	v_sub_u32_e32 v5, v4, v2
	v_cndmask_b32_e32 v4, v4, v5, vcc
	v_add_u32_e32 v5, 1, v1
	v_cmp_ge_u32_e32 vcc, v4, v2
	s_nop 1
	v_cndmask_b32_e32 v1, v1, v5, vcc
	v_mul_lo_u32 v4, v2, v1
	v_add_u32_e32 v2, v4, v2
	v_cmp_ne_u32_e32 vcc, v3, v2
	s_waitcnt lgkmcnt(0)
	v_add_u32_e32 v4, 1, v1
	v_mul_lo_u32 v4, v4, v0
	v_mov_b32_e32 v6, 0x21ff8
	ds_read_b32 v6, v6
	v_readlane_b32 s98, v253, 39
	v_readlane_b32 s99, v253, 40
	s_nop 4
	s_waitcnt lgkmcnt(0)
	v_readfirstlane_b32 s100, v6
	s_cmp_eq_u32 s100, 0
	s_cbranch_scc0 .Lxb_b2_full
	v_readlane_b32 s100, v254, 53
	s_bitcmp0_b32 s100, 0
	s_cbranch_scc0 .Lxb_b2_full
	s_cbranch_vccnz .Lxb_b2_lnl
	s_waitcnt vmcnt(0)
	global_atomic_add v177, v238, s[98:99]
	s_branch .Lxb_b2_done
.Lxb_b2_lnl:
	s_mov_b32 s100, 0
.Lxb_b2_lspin:
	global_atomic_add v5, v177, v177, s[4:5] sc0
	s_waitcnt vmcnt(0)
	v_cmp_ge_u32_e32 vcc, v5, v2
	s_cbranch_vccnz .Lxb_b2_done
	s_sleep 1
	s_add_i32 s100, s100, 1
	s_cmp_lt_u32 s100, 0x40000
	s_cbranch_scc1 .Lxb_b2_lspin
	s_branch .Lxb_b2_done
.Lxb_b2_full:
	s_cbranch_vccnz .Lxb_b2_nl
	buffer_wbl2 sc1
	s_waitcnt vmcnt(0)
	global_atomic_add v177, v238, s[98:99]
	s_mov_b32 s100, 0

; __device__ __forceinline__ unsigned xb_ld(unsigned* p)              { return __hip_atomic_load(p, __ATOMIC_RELAXED, __HIP_MEMORY_SCOPE_AGENT); }
; __device__ __forceinline__ unsigned xb_add(unsigned* p, unsigned v) { return __hip_atomic_fetch_add(p, v, __ATOMIC_RELAXED, __HIP_MEMORY_SCOPE_AGENT); }
; #define XB_SPIN(cond, bar) do { unsigned _sp = 0; while (cond) { __builtin_amdgcn_s_sleep(1); \
;     if ((++_sp & 255u) == 0u) { if (xb_ld(&(bar)[XB_TMO])) break; if (_sp > XB_SPIN_CAP) { atomicAdd(&(bar)[XB_TMO], 1u); break; } } } } while (0)
; __device__ __forceinline__ void xcd_barrier(const XcdBarrier& b) {
;     ...
;         unsigned nloc = b.st[0], nx = b.st[1];
;         if (nloc == 0u) { xcd_barrier_complete(bar, b.x, nloc, nx); b.st[0] = nloc; b.st[1] = nx; }
;         const unsigned old = xb_add(&bar[XB_XSUB(b.x)], 1u);
;         const unsigned gen = old / nloc;
;         if (old + 1u == (gen + 1u) * nloc) {
;             __builtin_amdgcn_fence(__ATOMIC_RELEASE, "agent");
;             asm volatile("s_waitcnt vmcnt(0)" ::: "memory");
;             const unsigned og = xb_add(&bar[XB_TOP], 1u);
;             const unsigned tg = og / nx;
;             if (og + 1u == (tg + 1u) * nx) xb_add(&bar[XB_TOPGEN], 1u);
;             else XB_SPIN(xb_ld(&bar[XB_TOPGEN]) == tg, bar);
;             __builtin_amdgcn_fence(__ATOMIC_ACQUIRE, "agent");
;             asm volatile("s_waitcnt vmcnt(0)" ::: "memory");
;         } else {
;             XB_SPIN(xb_ld(&bar[XB_TOPGEN]) == gen, bar);
;             __builtin_amdgcn_fence(__ATOMIC_ACQUIRE, "agent");
;             asm volatile("s_waitcnt vmcnt(0)" ::: "memory");
;         }
.LBB0_610:
	v_readlane_b32 s4, v253, 35
	v_readlane_b32 s5, v253, 36
	v_cvt_f32_u32_e32 v1, v2
	v_sub_u32_e32 v4, 0, v2
	v_rcp_iflag_f32_e32 v1, v1
	s_nop 1
	global_atomic_add v3, v177, v238, s[4:5] sc0
	buffer_inv sc1
	v_mul_f32_e32 v1, 0x4f7ffffe, v1
	v_cvt_u32_f32_e32 v1, v1
	v_mul_lo_u32 v4, v4, v1
	v_mul_hi_u32 v4, v1, v4
	v_add_u32_e32 v1, v1, v4
	s_waitcnt vmcnt(0)
	v_mul_hi_u32 v1, v3, v1
	v_mul_lo_u32 v4, v1, v2
	v_sub_u32_e32 v4, v3, v4
	v_add_u32_e32 v5, 1, v1
	v_cmp_ge_u32_e32 vcc, v4, v2
	v_add_u32_e32 v3, 1, v3
	s_nop 0
	v_cndmask_b32_e32 v1, v1, v5, vcc
	v_sub_u32_e32 v5, v4, v2
	v_cndmask_b32_e32 v4, v4, v5, vcc
	v_add_u32_e32 v5, 1, v1
	v_cmp_ge_u32_e32 vcc, v4, v2
	s_nop 1
	v_cndmask_b32_e32 v1, v1, v5, vcc
	v_mul_lo_u32 v4, v2, v1
	v_add_u32_e32 v2, v4, v2
	v_cmp_ne_u32_e32 vcc, v3, v2
	s_waitcnt lgkmcnt(0)
	v_add_u32_e32 v4, 1, v1
	v_mul_lo_u32 v4, v4, v0
	v_mov_b32_e32 v6, 0x21ff8
	ds_read_b32 v6, v6
	v_readlane_b32 s98, v253, 39
	v_readlane_b32 s99, v253, 40
	s_nop 4
	s_waitcnt lgkmcnt(0)
	v_readfirstlane_b32 s100, v6
	s_cmp_eq_u32 s100, 0
	s_cbranch_scc0 .Lxb_b3_full
	s_cbranch_vccnz .Lxb_b3_lnl
	s_waitcnt vmcnt(0)
	global_atomic_add v177, v238, s[98:99]
	s_branch .Lxb_b3_done
.Lxb_b3_lnl:
	s_mov_b32 s100, 0
.Lxb_b3_lspin:
	global_atomic_add v5, v177, v177, s[4:5] sc0
	s_waitcnt vmcnt(0)
	v_cmp_ge_u32_e32 vcc, v5, v2
	s_cbranch_vccnz .Lxb_b3_done
	s_sleep 1
	s_add_i32 s100, s100, 1
	s_cmp_lt_u32 s100, 0x40000
	s_cbranch_scc1 .Lxb_b3_lspin
	s_branch .Lxb_b3_done
.Lxb_b3_full:
	s_cbranch_vccnz .Lxb_b3_nl
	buffer_wbl2 sc1
	s_waitcnt vmcnt(0)
	global_atomic_add v177, v238, s[98:99]
	s_branch .Lxb_b3_poll
.Lxb_b3_nl:
.Lxb_b3_poll:
	s_mov_b32 s100, 0

; __device__ __forceinline__ unsigned xb_ld(unsigned* p)              { return __hip_atomic_load(p, __ATOMIC_RELAXED, __HIP_MEMORY_SCOPE_AGENT); }
; #define XB_SPIN(cond, bar) do { unsigned _sp = 0; while (cond) { __builtin_amdgcn_s_sleep(1); \
;     if ((++_sp & 255u) == 0u) { if (xb_ld(&(bar)[XB_TMO])) break; if (_sp > XB_SPIN_CAP) { atomicAdd(&(bar)[XB_TMO], 1u); break; } } } } while (0)
; __device__ __forceinline__ void xcd_barrier(const XcdBarrier& b) {
;     ...
;         } else {
;             XB_SPIN(xb_ld(&bar[XB_TOPGEN]) == gen, bar);
;             __builtin_amdgcn_fence(__ATOMIC_ACQUIRE, "agent");
;             asm volatile("s_waitcnt vmcnt(0)" ::: "memory");
.Lxb_b4_lnl:
	s_mov_b32 s100, 0
.Lxb_b4_lspin:
	global_atomic_add v5, v177, v177, s[4:5] sc0
	s_waitcnt vmcnt(0)
	v_cmp_ge_u32_e32 vcc, v5, v2
	s_cbranch_vccnz .Lxb_b4_done
	s_sleep 1
	s_add_i32 s100, s100, 1
	s_cmp_lt_u32 s100, 0x40000
	s_cbranch_scc1 .Lxb_b4_lspin
	s_branch .Lxb_b4_done

; __device__ __forceinline__ unsigned xb_ld(unsigned* p)              { return __hip_atomic_load(p, __ATOMIC_RELAXED, __HIP_MEMORY_SCOPE_AGENT); }
; #define XB_SPIN(cond, bar) do { unsigned _sp = 0; while (cond) { __builtin_amdgcn_s_sleep(1); \
;     if ((++_sp & 255u) == 0u) { if (xb_ld(&(bar)[XB_TMO])) break; if (_sp > XB_SPIN_CAP) { atomicAdd(&(bar)[XB_TMO], 1u); break; } } } } while (0)
; __device__ __forceinline__ void xcd_barrier(const XcdBarrier& b) {
;     ...
;         } else {
;             XB_SPIN(xb_ld(&bar[XB_TOPGEN]) == gen, bar);
;             __builtin_amdgcn_fence(__ATOMIC_ACQUIRE, "agent");
;             asm volatile("s_waitcnt vmcnt(0)" ::: "memory");
.Lxb_b5_lnl:
	s_mov_b32 s100, 0
.Lxb_b5_lspin:
	global_atomic_add v5, v177, v177, s[4:5] sc0
	s_waitcnt vmcnt(0)
	v_cmp_ge_u32_e32 vcc, v5, v2
	s_cbranch_vccnz .Lxb_b5_done
	s_sleep 1
	s_add_i32 s100, s100, 1
	s_cmp_lt_u32 s100, 0x40000
	s_cbranch_scc1 .Lxb_b5_lspin
	s_branch .Lxb_b5_done
